# attention c=1 epilogue: sub_norm gain loads hoisted into one burst
# speedup vs baseline: 1.0438x; 1.0006x over previous
; __device__ __forceinline__ float xhalf_sum(float v) { auto rr = __builtin_amdgcn_permlane32_swap(__float_as_uint(v), __float_as_uint(v), false, false); return __uint_as_float(rr[0]) + __uint_as_float(rr[1]); }
; __device__ __forceinline__ void attn_phase(const Args& a, LAS unsigned char* lds, const bf16* Qn, const bf16* Kn, const bf16* Vt, bf16* O, float* stash, int tid, int lane, int wave) {
;     ...
;             const float inv = 1.0f / xhalf_sum(lsum);
;             int oz; asm volatile("v_mov_b32 %0, 0" : "=v"(oz));
;             float* st = stash + ((size_t)blockIdx.x * 8 + wave) * 4096 + lane + oz;
;             if (c == 0) {
; #pragma unroll
;                 for (int i = 0; i < 4; ++i)
; #pragma unroll
;                     for (int r = 0; r < 16; ++r) __builtin_nontemporal_store(o[i][r] * inv, &st[(i * 16 + r) * 64]);
;             } else {
;                 float ss = 0.f;
; #pragma unroll
;                 for (int i = 0; i < 4; ++i) {
;                     float tv[16];
; #pragma unroll
;                     for (int r = 0; r < 16; ++r) tv[r] = st[(i * 16 + r) * 64];
;                     asm volatile("" ::: "memory");
; #pragma unroll
;                     for (int r = 0; r < 16; ++r) { const float v = tv[r] - lam * (o[i][r] * inv); o[i][r] = v; ss += v * v; }
;                 }
.LBB0_132:
	v_mov_b32_e32 v0, v197
	s_nop 1
	v_permlane32_swap_b32_e32 v197, v0
	v_add_f32_e32 v0, v197, v0
	v_div_scale_f32 v2, s[20:21], v0, v0, 1.0
	v_rcp_f32_e32 v3, v2
	s_mov_b64 s[20:21], -1
	s_movk_i32 s2, 0x1000
	v_fma_f32 v4, -v2, v3, 1.0
	v_fmac_f32_e32 v3, v4, v3
	v_div_scale_f32 v4, vcc, 1.0, v0, 1.0
	v_mul_f32_e32 v5, v4, v3
	v_fma_f32 v6, -v2, v5, v4
	v_fmac_f32_e32 v5, v6, v3
	v_fma_f32 v2, -v2, v5, v4
	v_div_fmas_f32 v2, v2, v3, v5
	v_div_fixup_f32 v0, v2, v0, 1.0
	v_mov_b32 v2, 0
	s_andn2_b64 vcc, exec, s[16:17]
	v_ashrrev_i32_e32 v3, 31, v2
	v_lshl_add_u64 v[6:7], v[2:3], 2, v[168:169]
	s_cbranch_vccnz .LBB0_134
	global_load_dword v4, v[6:7], off
	global_load_dword v5, v[6:7], off offset:256
	global_load_dword v8, v[6:7], off offset:512
	global_load_dword v9, v[6:7], off offset:768
	global_load_dword v10, v[6:7], off offset:1024
	global_load_dword v11, v[6:7], off offset:1280
	global_load_dword v14, v[6:7], off offset:1536
	global_load_dword v15, v[6:7], off offset:1792
	global_load_dword v80, v[6:7], off offset:2048
	global_load_dword v81, v[6:7], off offset:2304
	global_load_dword v88, v[6:7], off offset:2560
	global_load_dword v89, v[6:7], off offset:2816
	global_load_dword v90, v[6:7], off offset:3072
	global_load_dword v91, v[6:7], off offset:3328
	global_load_dword v92, v[6:7], off offset:3584
	global_load_dword v93, v[6:7], off offset:3840
	v_pk_mul_f32 v[12:13], v[64:65], v[0:1] op_sel_hi:[1,0]
	s_movk_i32 s20, 0x2000
	v_add_u32_e32 v2, v196, v2
	s_waitcnt vmcnt(14)
	v_pk_fma_f32 v[82:83], v[156:157], v[12:13], v[4:5] neg_lo:[1,0,0] neg_hi:[1,0,0]
	s_nop 0
	v_mul_f32_e32 v4, v83, v83
	v_pk_mul_f32 v[12:13], v[66:67], v[0:1] op_sel_hi:[1,0]
	v_pk_fma_f32 v[4:5], v[82:83], v[82:83], v[4:5] op_sel_hi:[1,1,0]
	s_waitcnt vmcnt(12)
	v_pk_fma_f32 v[86:87], v[156:157], v[12:13], v[8:9] neg_lo:[1,0,0] neg_hi:[1,0,0]
	s_nop 0
	v_pk_fma_f32 v[4:5], v[86:87], v[86:87], v[4:5]
	v_mul_f32_e32 v8, v87, v87
	v_pk_add_f32 v[4:5], v[4:5], v[8:9] op_sel_hi:[1,0]
	v_pk_mul_f32 v[8:9], v[68:69], v[0:1] op_sel_hi:[1,0]
	s_waitcnt vmcnt(10)
	v_pk_fma_f32 v[12:13], v[156:157], v[8:9], v[10:11] neg_lo:[1,0,0] neg_hi:[1,0,0]
	s_nop 0
	v_pk_fma_f32 v[4:5], v[12:13], v[12:13], v[4:5]
	v_mul_f32_e32 v8, v13, v13
	v_pk_add_f32 v[4:5], v[4:5], v[8:9] op_sel_hi:[1,0]
	v_pk_mul_f32 v[8:9], v[70:71], v[0:1] op_sel_hi:[1,0]
	s_waitcnt vmcnt(8)
	v_pk_fma_f32 v[84:85], v[156:157], v[8:9], v[14:15] neg_lo:[1,0,0] neg_hi:[1,0,0]
	s_nop 0
	v_pk_fma_f32 v[4:5], v[84:85], v[84:85], v[4:5]
	v_mul_f32_e32 v8, v85, v85
	v_pk_add_f32 v[4:5], v[4:5], v[8:9] op_sel_hi:[1,0]
	v_pk_mul_f32 v[8:9], v[72:73], v[0:1] op_sel_hi:[1,0]
	s_waitcnt vmcnt(6)
	v_pk_fma_f32 v[10:11], v[156:157], v[8:9], v[80:81] neg_lo:[1,0,0] neg_hi:[1,0,0]
	s_nop 0
	v_pk_fma_f32 v[4:5], v[10:11], v[10:11], v[4:5]
	v_mul_f32_e32 v8, v11, v11
	v_pk_add_f32 v[4:5], v[4:5], v[8:9] op_sel_hi:[1,0]
	v_pk_mul_f32 v[8:9], v[74:75], v[0:1] op_sel_hi:[1,0]
	s_waitcnt vmcnt(4)
	v_pk_fma_f32 v[80:81], v[156:157], v[8:9], v[88:89] neg_lo:[1,0,0] neg_hi:[1,0,0]
	s_nop 0
	v_pk_fma_f32 v[4:5], v[80:81], v[80:81], v[4:5]
	v_mul_f32_e32 v8, v81, v81
	v_pk_add_f32 v[4:5], v[4:5], v[8:9] op_sel_hi:[1,0]
	v_pk_mul_f32 v[8:9], v[76:77], v[0:1] op_sel_hi:[1,0]
	s_waitcnt vmcnt(2)
	v_pk_fma_f32 v[8:9], v[156:157], v[8:9], v[90:91] neg_lo:[1,0,0] neg_hi:[1,0,0]
	s_nop 0
	v_pk_fma_f32 v[4:5], v[8:9], v[8:9], v[4:5]
	v_mul_f32_e32 v14, v9, v9
	v_pk_add_f32 v[4:5], v[4:5], v[14:15] op_sel_hi:[1,0]
	v_pk_mul_f32 v[14:15], v[78:79], v[0:1] op_sel_hi:[1,0]
	s_waitcnt vmcnt(0)
	v_pk_fma_f32 v[14:15], v[156:157], v[14:15], v[92:93] neg_lo:[1,0,0] neg_hi:[1,0,0]
	s_nop 0
	v_pk_fma_f32 v[4:5], v[14:15], v[14:15], v[4:5]
	v_mul_f32_e32 v88, v15, v15
	v_pk_add_f32 v[90:91], v[4:5], v[88:89] op_sel_hi:[1,0]
	v_add_co_u32_e32 v88, vcc, s2, v6
	s_nop 1
	v_addc_co_u32_e32 v89, vcc, 0, v7, vcc
	v_add_co_u32_e32 v4, vcc, s20, v6
	s_movk_i32 s20, 0x3000
	s_nop 0
	v_addc_co_u32_e32 v5, vcc, 0, v7, vcc
	global_load_dword v92, v[4:5], off offset:-4096
	global_load_dword v93, v[88:89], off offset:256
	global_load_dword v94, v[88:89], off offset:512
	global_load_dword v95, v[88:89], off offset:768
	global_load_dword v96, v[88:89], off offset:1024
	global_load_dword v97, v[88:89], off offset:1280
	global_load_dword v98, v[88:89], off offset:1536
	global_load_dword v99, v[88:89], off offset:1792
	global_load_dword v104, v[88:89], off offset:2048
	global_load_dword v105, v[88:89], off offset:2304
	global_load_dword v106, v[88:89], off offset:2560
	global_load_dword v107, v[88:89], off offset:2816
	global_load_dword v108, v[88:89], off offset:3072
	global_load_dword v109, v[88:89], off offset:3328
	global_load_dword v110, v[88:89], off offset:3584
	global_load_dword v111, v[88:89], off offset:3840
	v_pk_mul_f32 v[88:89], v[48:49], v[0:1] op_sel_hi:[1,0]
	s_waitcnt vmcnt(14)
	v_pk_fma_f32 v[88:89], v[156:157], v[88:89], v[92:93] neg_lo:[1,0,0] neg_hi:[1,0,0]
	s_nop 0
	v_pk_fma_f32 v[90:91], v[88:89], v[88:89], v[90:91]
	v_mul_f32_e32 v92, v89, v89
	v_pk_add_f32 v[90:91], v[90:91], v[92:93] op_sel_hi:[1,0]
	v_pk_mul_f32 v[92:93], v[50:51], v[0:1] op_sel_hi:[1,0]
	s_waitcnt vmcnt(12)
	v_pk_fma_f32 v[102:103], v[156:157], v[92:93], v[94:95] neg_lo:[1,0,0] neg_hi:[1,0,0]
	s_nop 0
	v_pk_fma_f32 v[90:91], v[102:103], v[102:103], v[90:91]
	v_mul_f32_e32 v92, v103, v103
	v_pk_add_f32 v[90:91], v[90:91], v[92:93] op_sel_hi:[1,0]
	v_pk_mul_f32 v[92:93], v[52:53], v[0:1] op_sel_hi:[1,0]
	s_waitcnt vmcnt(10)
; __device__ __forceinline__ void attn_phase(const Args& a, LAS unsigned char* lds, const bf16* Qn, const bf16* Kn, const bf16* Vt, bf16* O, float* stash, int tid, int lane, int wave) {
;     ...
;                 float ss = 0.f;
; #pragma unroll
;                 for (int i = 0; i < 4; ++i) {
;                     float tv[16];
; #pragma unroll
;                     for (int r = 0; r < 16; ++r) tv[r] = st[(i * 16 + r) * 64];
;                     asm volatile("" ::: "memory");
; #pragma unroll
;                     for (int r = 0; r < 16; ++r) { const float v = tv[r] - lam * (o[i][r] * inv); o[i][r] = v; ss += v * v; }
;                 }
	v_pk_fma_f32 v[94:95], v[156:157], v[92:93], v[96:97] neg_lo:[1,0,0] neg_hi:[1,0,0]
	s_nop 0
	v_pk_fma_f32 v[90:91], v[94:95], v[94:95], v[90:91]
	v_mul_f32_e32 v92, v95, v95
	v_pk_add_f32 v[90:91], v[90:91], v[92:93] op_sel_hi:[1,0]
	v_pk_mul_f32 v[92:93], v[54:55], v[0:1] op_sel_hi:[1,0]
	s_waitcnt vmcnt(8)
	v_pk_fma_f32 v[100:101], v[156:157], v[92:93], v[98:99] neg_lo:[1,0,0] neg_hi:[1,0,0]
	s_nop 0
	v_pk_fma_f32 v[90:91], v[100:101], v[100:101], v[90:91]
	v_mul_f32_e32 v92, v101, v101
	v_pk_add_f32 v[90:91], v[90:91], v[92:93] op_sel_hi:[1,0]
	v_pk_mul_f32 v[92:93], v[56:57], v[0:1] op_sel_hi:[1,0]
	s_waitcnt vmcnt(6)
	v_pk_fma_f32 v[92:93], v[156:157], v[92:93], v[104:105] neg_lo:[1,0,0] neg_hi:[1,0,0]
	s_nop 0
	v_pk_fma_f32 v[90:91], v[92:93], v[92:93], v[90:91]
	v_mul_f32_e32 v96, v93, v93
	v_pk_add_f32 v[90:91], v[90:91], v[96:97] op_sel_hi:[1,0]
	v_pk_mul_f32 v[96:97], v[58:59], v[0:1] op_sel_hi:[1,0]
	s_waitcnt vmcnt(4)
	v_pk_fma_f32 v[98:99], v[156:157], v[96:97], v[106:107] neg_lo:[1,0,0] neg_hi:[1,0,0]
	s_nop 0
	v_pk_fma_f32 v[90:91], v[98:99], v[98:99], v[90:91]
	v_mul_f32_e32 v96, v99, v99
	v_pk_add_f32 v[96:97], v[90:91], v[96:97] op_sel_hi:[1,0]
	v_pk_mul_f32 v[90:91], v[60:61], v[0:1] op_sel_hi:[1,0]
	s_waitcnt vmcnt(2)
	v_pk_fma_f32 v[90:91], v[156:157], v[90:91], v[108:109] neg_lo:[1,0,0] neg_hi:[1,0,0]
	s_nop 0
	v_pk_fma_f32 v[96:97], v[90:91], v[90:91], v[96:97]
	v_mul_f32_e32 v104, v91, v91
	v_pk_add_f32 v[104:105], v[96:97], v[104:105] op_sel_hi:[1,0]
	v_pk_mul_f32 v[96:97], v[62:63], v[0:1] op_sel_hi:[1,0]
	s_waitcnt vmcnt(0)
	v_pk_fma_f32 v[96:97], v[156:157], v[96:97], v[110:111] neg_lo:[1,0,0] neg_hi:[1,0,0]
	s_nop 0
	v_pk_fma_f32 v[104:105], v[96:97], v[96:97], v[104:105]
	v_mul_f32_e32 v106, v97, v97
	v_pk_add_f32 v[104:105], v[104:105], v[106:107] op_sel_hi:[1,0]
	global_load_dword v106, v[4:5], off
	global_load_dword v107, v[4:5], off offset:256
	global_load_dword v108, v[4:5], off offset:512
	global_load_dword v109, v[4:5], off offset:768
	global_load_dword v110, v[4:5], off offset:1024
	global_load_dword v111, v[4:5], off offset:1280
	global_load_dword v114, v[4:5], off offset:1536
	global_load_dword v115, v[4:5], off offset:1792
	global_load_dword v120, v[4:5], off offset:2048
	global_load_dword v121, v[4:5], off offset:2304
	global_load_dword v122, v[4:5], off offset:2560
	global_load_dword v123, v[4:5], off offset:2816
	global_load_dword v124, v[4:5], off offset:3072
	global_load_dword v125, v[4:5], off offset:3328
	global_load_dword v126, v[4:5], off offset:3584
	global_load_dword v127, v[4:5], off offset:3840
	v_pk_mul_f32 v[4:5], v[32:33], v[0:1] op_sel_hi:[1,0]
	s_waitcnt vmcnt(14)
	v_pk_fma_f32 v[112:113], v[156:157], v[4:5], v[106:107] neg_lo:[1,0,0] neg_hi:[1,0,0]
	s_nop 0
	v_pk_fma_f32 v[4:5], v[112:113], v[112:113], v[104:105]
	v_mul_f32_e32 v104, v113, v113
	v_pk_add_f32 v[4:5], v[4:5], v[104:105] op_sel_hi:[1,0]
	v_pk_mul_f32 v[104:105], v[34:35], v[0:1] op_sel_hi:[1,0]
	s_waitcnt vmcnt(12)
	v_pk_fma_f32 v[118:119], v[156:157], v[104:105], v[108:109] neg_lo:[1,0,0] neg_hi:[1,0,0]
	s_nop 0
	v_pk_fma_f32 v[4:5], v[118:119], v[118:119], v[4:5]
	v_mul_f32_e32 v104, v119, v119
	v_pk_add_f32 v[4:5], v[4:5], v[104:105] op_sel_hi:[1,0]
	v_pk_mul_f32 v[104:105], v[36:37], v[0:1] op_sel_hi:[1,0]
	s_waitcnt vmcnt(10)
	v_pk_fma_f32 v[108:109], v[156:157], v[104:105], v[110:111] neg_lo:[1,0,0] neg_hi:[1,0,0]
	s_nop 0
	v_pk_fma_f32 v[4:5], v[108:109], v[108:109], v[4:5]
	v_mul_f32_e32 v104, v109, v109
	v_pk_add_f32 v[4:5], v[4:5], v[104:105] op_sel_hi:[1,0]
	v_pk_mul_f32 v[104:105], v[38:39], v[0:1] op_sel_hi:[1,0]
	s_waitcnt vmcnt(8)
	v_pk_fma_f32 v[116:117], v[156:157], v[104:105], v[114:115] neg_lo:[1,0,0] neg_hi:[1,0,0]
	s_nop 0
	v_pk_fma_f32 v[4:5], v[116:117], v[116:117], v[4:5]
	v_mul_f32_e32 v104, v117, v117
	v_pk_add_f32 v[4:5], v[4:5], v[104:105] op_sel_hi:[1,0]
	v_pk_mul_f32 v[104:105], v[40:41], v[0:1] op_sel_hi:[1,0]
	s_waitcnt vmcnt(6)
	v_pk_fma_f32 v[106:107], v[156:157], v[104:105], v[120:121] neg_lo:[1,0,0] neg_hi:[1,0,0]
	s_nop 0
	v_pk_fma_f32 v[4:5], v[106:107], v[106:107], v[4:5]
	v_mul_f32_e32 v104, v107, v107
	v_pk_add_f32 v[4:5], v[4:5], v[104:105] op_sel_hi:[1,0]
	v_pk_mul_f32 v[104:105], v[42:43], v[0:1] op_sel_hi:[1,0]
	s_waitcnt vmcnt(4)
	v_pk_fma_f32 v[114:115], v[156:157], v[104:105], v[122:123] neg_lo:[1,0,0] neg_hi:[1,0,0]
	s_nop 0
	v_pk_fma_f32 v[4:5], v[114:115], v[114:115], v[4:5]
	v_mul_f32_e32 v104, v115, v115
	v_pk_add_f32 v[4:5], v[4:5], v[104:105] op_sel_hi:[1,0]
	v_pk_mul_f32 v[104:105], v[44:45], v[0:1] op_sel_hi:[1,0]
	s_waitcnt vmcnt(2)
	v_pk_fma_f32 v[104:105], v[156:157], v[104:105], v[124:125] neg_lo:[1,0,0] neg_hi:[1,0,0]
	s_nop 0
	v_pk_fma_f32 v[4:5], v[104:105], v[104:105], v[4:5]
	v_mul_f32_e32 v110, v105, v105
	v_pk_add_f32 v[4:5], v[4:5], v[110:111] op_sel_hi:[1,0]
	v_pk_mul_f32 v[110:111], v[46:47], v[0:1] op_sel_hi:[1,0]
	s_waitcnt vmcnt(0)
	v_pk_fma_f32 v[110:111], v[156:157], v[110:111], v[126:127] neg_lo:[1,0,0] neg_hi:[1,0,0]
	s_nop 0
	v_pk_fma_f32 v[4:5], v[110:111], v[110:111], v[4:5]
	v_mul_f32_e32 v120, v111, v111
	v_pk_add_f32 v[4:5], v[4:5], v[120:121] op_sel_hi:[1,0]
	v_add_co_u32_e32 v120, vcc, s20, v6
	s_nop 1
	v_addc_co_u32_e32 v121, vcc, 0, v7, vcc
	global_load_dword v122, v[120:121], off
	global_load_dword v123, v[120:121], off offset:256
	global_load_dword v124, v[120:121], off offset:512
	global_load_dword v125, v[120:121], off offset:768
	global_load_dword v126, v[120:121], off offset:1024
	global_load_dword v127, v[120:121], off offset:1280
	global_load_dword v130, v[120:121], off offset:1536
	global_load_dword v131, v[120:121], off offset:1792
	global_load_dword v136, v[120:121], off offset:2048
	global_load_dword v137, v[120:121], off offset:2304
	global_load_dword v138, v[120:121], off offset:2560
	global_load_dword v139, v[120:121], off offset:2816
	global_load_dword v140, v[120:121], off offset:3072
	global_load_dword v141, v[120:121], off offset:3328
	global_load_dword v142, v[120:121], off offset:3584
	global_load_dword v143, v[120:121], off offset:3840
	v_pk_mul_f32 v[120:121], v[16:17], v[0:1] op_sel_hi:[1,0]
	s_waitcnt vmcnt(14)
; __device__ __forceinline__ float xhalf_sum(float v) { auto rr = __builtin_amdgcn_permlane32_swap(__float_as_uint(v), __float_as_uint(v), false, false); return __uint_as_float(rr[0]) + __uint_as_float(rr[1]); }
; __device__ __forceinline__ void attn_phase(const Args& a, LAS unsigned char* lds, const bf16* Qn, const bf16* Kn, const bf16* Vt, bf16* O, float* stash, int tid, int lane, int wave) {
;     ...
;                     for (int r = 0; r < 16; ++r) { const float v = tv[r] - lam * (o[i][r] * inv); o[i][r] = v; ss += v * v; }
;                 }
;                 ss = xhalf_sum(ss);
;                 const float rs = rsqrtf(ss * (1.f / 128.f) + 1e-5f) * (1.0f - LAM_INIT);
;                 bf16* op = O + (size_t)(b * SEQ + 256 * qb + 32 * wave + n32 + oz) * DM + h * 128 + 4 * hi;
; #pragma unroll
;                 for (int i = 0; i < 4; ++i)
; #pragma unroll
;                     for (int r4 = 0; r4 < 4; ++r4) {
;                         const f32x4 sn = *(const f32x4*)(subn + 32 * i + 8 * r4 + 4 * hi);
	v_pk_fma_f32 v[128:129], v[156:157], v[120:121], v[122:123] neg_lo:[1,0,0] neg_hi:[1,0,0]
	s_nop 0
	v_pk_fma_f32 v[4:5], v[128:129], v[128:129], v[4:5]
	v_mul_f32_e32 v120, v129, v129
	v_pk_add_f32 v[4:5], v[4:5], v[120:121] op_sel_hi:[1,0]
	v_pk_mul_f32 v[120:121], v[18:19], v[0:1] op_sel_hi:[1,0]
	s_waitcnt vmcnt(12)
	v_pk_fma_f32 v[134:135], v[156:157], v[120:121], v[124:125] neg_lo:[1,0,0] neg_hi:[1,0,0]
	s_nop 0
	v_pk_fma_f32 v[4:5], v[134:135], v[134:135], v[4:5]
	v_mul_f32_e32 v120, v135, v135
	v_pk_add_f32 v[4:5], v[4:5], v[120:121] op_sel_hi:[1,0]
	v_pk_mul_f32 v[120:121], v[20:21], v[0:1] op_sel_hi:[1,0]
	s_waitcnt vmcnt(10)
	v_pk_fma_f32 v[124:125], v[156:157], v[120:121], v[126:127] neg_lo:[1,0,0] neg_hi:[1,0,0]
	s_nop 0
	v_pk_fma_f32 v[4:5], v[124:125], v[124:125], v[4:5]
	v_mul_f32_e32 v120, v125, v125
	v_pk_add_f32 v[4:5], v[4:5], v[120:121] op_sel_hi:[1,0]
	v_pk_mul_f32 v[120:121], v[22:23], v[0:1] op_sel_hi:[1,0]
	s_waitcnt vmcnt(8)
	v_pk_fma_f32 v[132:133], v[156:157], v[120:121], v[130:131] neg_lo:[1,0,0] neg_hi:[1,0,0]
	s_nop 0
	v_pk_fma_f32 v[4:5], v[132:133], v[132:133], v[4:5]
	v_mul_f32_e32 v120, v133, v133
	v_pk_add_f32 v[4:5], v[4:5], v[120:121] op_sel_hi:[1,0]
	v_pk_mul_f32 v[120:121], v[24:25], v[0:1] op_sel_hi:[1,0]
	s_waitcnt vmcnt(6)
	v_pk_fma_f32 v[122:123], v[156:157], v[120:121], v[136:137] neg_lo:[1,0,0] neg_hi:[1,0,0]
	s_nop 0
	v_pk_fma_f32 v[4:5], v[122:123], v[122:123], v[4:5]
	v_mul_f32_e32 v120, v123, v123
	v_pk_add_f32 v[4:5], v[4:5], v[120:121] op_sel_hi:[1,0]
	v_pk_mul_f32 v[120:121], v[26:27], v[0:1] op_sel_hi:[1,0]
	s_waitcnt vmcnt(4)
	v_pk_fma_f32 v[130:131], v[156:157], v[120:121], v[138:139] neg_lo:[1,0,0] neg_hi:[1,0,0]
	s_nop 0
	v_pk_fma_f32 v[4:5], v[130:131], v[130:131], v[4:5]
	v_mul_f32_e32 v120, v131, v131
	v_pk_add_f32 v[4:5], v[4:5], v[120:121] op_sel_hi:[1,0]
	v_pk_mul_f32 v[120:121], v[28:29], v[0:1] op_sel_hi:[1,0]
	s_waitcnt vmcnt(2)
	v_pk_fma_f32 v[120:121], v[156:157], v[120:121], v[140:141] neg_lo:[1,0,0] neg_hi:[1,0,0]
	s_nop 0
	v_pk_fma_f32 v[4:5], v[120:121], v[120:121], v[4:5]
	v_mul_f32_e32 v126, v121, v121
	v_pk_add_f32 v[4:5], v[4:5], v[126:127] op_sel_hi:[1,0]
	v_pk_mul_f32 v[126:127], v[30:31], v[0:1] op_sel_hi:[1,0]
	s_waitcnt vmcnt(0)
	global_load_dwordx4 v[16:19], v[172:173], off
	global_load_dwordx4 v[20:23], v[172:173], off offset:32
	global_load_dwordx4 v[24:27], v[172:173], off offset:64
	global_load_dwordx4 v[28:31], v[172:173], off offset:96
	global_load_dwordx4 v[32:35], v[172:173], off offset:128
	global_load_dwordx4 v[36:39], v[172:173], off offset:160
	global_load_dwordx4 v[40:43], v[172:173], off offset:192
	global_load_dwordx4 v[44:47], v[172:173], off offset:224
	global_load_dwordx4 v[48:51], v[172:173], off offset:256
	global_load_dwordx4 v[52:55], v[172:173], off offset:288
	global_load_dwordx4 v[56:59], v[172:173], off offset:320
	global_load_dwordx4 v[60:63], v[172:173], off offset:352
	global_load_dwordx4 v[64:67], v[172:173], off offset:384
	global_load_dwordx4 v[68:71], v[172:173], off offset:416
	global_load_dwordx4 v[72:75], v[172:173], off offset:448
	global_load_dwordx4 v[76:79], v[172:173], off offset:480
	v_pk_fma_f32 v[126:127], v[156:157], v[126:127], v[142:143] neg_lo:[1,0,0] neg_hi:[1,0,0]
	s_nop 0
	v_pk_fma_f32 v[4:5], v[126:127], v[126:127], v[4:5]
	v_mul_f32_e32 v136, v127, v127
	v_pk_add_f32 v[4:5], v[4:5], v[136:137] op_sel_hi:[1,0]
	s_nop 0
	v_mov_b32_e32 v3, v4
	s_nop 1
	v_permlane32_swap_b32_e32 v4, v3
	v_add_f32_e32 v3, v4, v3
	v_fmamk_f32 v3, v3, 0x3c000000, v250
	v_cmp_gt_f32_e32 vcc, s37, v3
	v_mul_f32_e32 v4, 0x4b800000, v3
	s_nop 0
	v_cndmask_b32_e32 v3, v3, v4, vcc
	v_rsq_f32_e32 v3, v3
	s_nop 0
	v_mul_f32_e32 v4, 0x45800000, v3
	v_cndmask_b32_e32 v3, v3, v4, vcc
	v_mul_f32_e32 v138, 0x3f24fd5c, v3
	v_ashrrev_i32_e32 v3, 31, v2
	v_lshlrev_b64 v[2:3], 11, v[2:3]
	v_lshl_add_u64 v[136:137], v[182:183], 0, v[2:3]
	v_pk_mul_f32 v[82:83], v[82:83], v[138:139] op_sel_hi:[1,0]
	v_pk_mul_f32 v[86:87], v[86:87], v[138:139] op_sel_hi:[1,0]
	v_pk_mul_f32 v[12:13], v[12:13], v[138:139] op_sel_hi:[1,0]
	v_pk_mul_f32 v[10:11], v[10:11], v[138:139] op_sel_hi:[1,0]
	v_pk_mul_f32 v[8:9], v[8:9], v[138:139] op_sel_hi:[1,0]
	s_waitcnt vmcnt(0)
; __device__ __forceinline__ u32x2 pk4(f32x4 v) { u32x2 r; r.x = pk2(v.x, v.y); r.y = pk2(v.z, v.w); return r; }
; __device__ __forceinline__ void attn_phase(const Args& a, LAS unsigned char* lds, const bf16* Qn, const bf16* Kn, const bf16* Vt, bf16* O, float* stash, int tid, int lane, int wave) {
;     ...
;                 bf16* op = O + (size_t)(b * SEQ + 256 * qb + 32 * wave + n32 + oz) * DM + h * 128 + 4 * hi;
; #pragma unroll
;                 for (int i = 0; i < 4; ++i)
; #pragma unroll
;                     for (int r4 = 0; r4 < 4; ++r4) {
;                         const f32x4 sn = *(const f32x4*)(subn + 32 * i + 8 * r4 + 4 * hi);
;                         const f32x4 v = (f32x4){o[i][4 * r4], o[i][4 * r4 + 1], o[i][4 * r4 + 2], o[i][4 * r4 + 3]} * rs * sn;
;                         *(u32x2*)(op + 32 * i + 8 * r4) = pk4(v);
;                     }
	v_pk_mul_f32 v[18:19], v[18:19], v[86:87]
	v_pk_mul_f32 v[16:17], v[16:17], v[82:83]
	v_pk_mul_f32 v[82:83], v[84:85], v[138:139] op_sel_hi:[1,0]
	v_cvt_pk_bf16_f32 v16, v16, v17
	v_cvt_pk_bf16_f32 v17, v18, v19
	global_store_dwordx2 v[136:137], v[16:17], off
	v_pk_mul_f32 v[22:23], v[22:23], v[82:83]
	v_pk_mul_f32 v[20:21], v[20:21], v[12:13]
	v_pk_mul_f32 v[12:13], v[80:81], v[138:139] op_sel_hi:[1,0]
	v_cvt_pk_bf16_f32 v20, v20, v21
	v_cvt_pk_bf16_f32 v21, v22, v23
	global_store_dwordx2 v[136:137], v[20:21], off offset:16
	v_pk_mul_f32 v[26:27], v[26:27], v[12:13]
	v_pk_mul_f32 v[24:25], v[24:25], v[10:11]
	v_pk_mul_f32 v[10:11], v[14:15], v[138:139] op_sel_hi:[1,0]
	v_cvt_pk_bf16_f32 v24, v24, v25
	v_cvt_pk_bf16_f32 v25, v26, v27
	global_store_dwordx2 v[136:137], v[24:25], off offset:32
	v_pk_mul_f32 v[30:31], v[30:31], v[10:11]
	v_pk_mul_f32 v[28:29], v[28:29], v[8:9]
	v_pk_mul_f32 v[8:9], v[88:89], v[138:139] op_sel_hi:[1,0]
	v_cvt_pk_bf16_f32 v28, v28, v29
	v_cvt_pk_bf16_f32 v29, v30, v31
	global_store_dwordx2 v[136:137], v[28:29], off offset:48
	v_pk_mul_f32 v[10:11], v[102:103], v[138:139] op_sel_hi:[1,0]
	v_pk_mul_f32 v[32:33], v[32:33], v[8:9]
	v_pk_mul_f32 v[34:35], v[34:35], v[10:11]
	v_cvt_pk_bf16_f32 v32, v32, v33
	v_cvt_pk_bf16_f32 v33, v34, v35
	global_store_dwordx2 v[136:137], v[32:33], off offset:64
	v_pk_mul_f32 v[8:9], v[94:95], v[138:139] op_sel_hi:[1,0]
	v_pk_mul_f32 v[10:11], v[100:101], v[138:139] op_sel_hi:[1,0]
	v_pk_mul_f32 v[36:37], v[36:37], v[8:9]
	v_pk_mul_f32 v[38:39], v[38:39], v[10:11]
	v_cvt_pk_bf16_f32 v36, v36, v37
	v_cvt_pk_bf16_f32 v37, v38, v39
	global_store_dwordx2 v[136:137], v[36:37], off offset:80
	v_pk_mul_f32 v[8:9], v[92:93], v[138:139] op_sel_hi:[1,0]
	v_pk_mul_f32 v[10:11], v[98:99], v[138:139] op_sel_hi:[1,0]
	v_pk_mul_f32 v[40:41], v[40:41], v[8:9]
	v_pk_mul_f32 v[42:43], v[42:43], v[10:11]
	v_cvt_pk_bf16_f32 v40, v40, v41
	v_cvt_pk_bf16_f32 v41, v42, v43
	global_store_dwordx2 v[136:137], v[40:41], off offset:96
	v_pk_mul_f32 v[8:9], v[90:91], v[138:139] op_sel_hi:[1,0]
	v_pk_mul_f32 v[10:11], v[96:97], v[138:139] op_sel_hi:[1,0]
	v_pk_mul_f32 v[44:45], v[8:9], v[44:45]
	v_pk_mul_f32 v[46:47], v[10:11], v[46:47]
	v_cvt_pk_bf16_f32 v44, v44, v45
	v_cvt_pk_bf16_f32 v45, v46, v47
	global_store_dwordx2 v[136:137], v[44:45], off offset:112
	v_pk_mul_f32 v[8:9], v[112:113], v[138:139] op_sel_hi:[1,0]
	v_pk_mul_f32 v[10:11], v[118:119], v[138:139] op_sel_hi:[1,0]
	v_pk_mul_f32 v[48:49], v[8:9], v[48:49]
	v_pk_mul_f32 v[50:51], v[10:11], v[50:51]
	v_cvt_pk_bf16_f32 v48, v48, v49
	v_cvt_pk_bf16_f32 v49, v50, v51
	global_store_dwordx2 v[136:137], v[48:49], off offset:128
	v_pk_mul_f32 v[8:9], v[108:109], v[138:139] op_sel_hi:[1,0]
	v_pk_mul_f32 v[10:11], v[116:117], v[138:139] op_sel_hi:[1,0]
	v_pk_mul_f32 v[52:53], v[8:9], v[52:53]
	v_pk_mul_f32 v[54:55], v[10:11], v[54:55]
	v_cvt_pk_bf16_f32 v52, v52, v53
	v_cvt_pk_bf16_f32 v53, v54, v55
	global_store_dwordx2 v[136:137], v[52:53], off offset:144
	v_pk_mul_f32 v[8:9], v[106:107], v[138:139] op_sel_hi:[1,0]
	v_pk_mul_f32 v[10:11], v[114:115], v[138:139] op_sel_hi:[1,0]
	v_pk_mul_f32 v[56:57], v[8:9], v[56:57]
	v_pk_mul_f32 v[58:59], v[10:11], v[58:59]
	v_cvt_pk_bf16_f32 v56, v56, v57
	v_cvt_pk_bf16_f32 v57, v58, v59
	global_store_dwordx2 v[136:137], v[56:57], off offset:160
	v_pk_mul_f32 v[8:9], v[104:105], v[138:139] op_sel_hi:[1,0]
	v_pk_mul_f32 v[10:11], v[110:111], v[138:139] op_sel_hi:[1,0]
	v_pk_mul_f32 v[60:61], v[8:9], v[60:61]
	v_pk_mul_f32 v[62:63], v[10:11], v[62:63]
	v_cvt_pk_bf16_f32 v60, v60, v61
	v_cvt_pk_bf16_f32 v61, v62, v63
	global_store_dwordx2 v[136:137], v[60:61], off offset:176
	v_pk_mul_f32 v[8:9], v[128:129], v[138:139] op_sel_hi:[1,0]
	v_pk_mul_f32 v[10:11], v[134:135], v[138:139] op_sel_hi:[1,0]
	v_pk_mul_f32 v[64:65], v[8:9], v[64:65]
	v_pk_mul_f32 v[66:67], v[10:11], v[66:67]
	v_cvt_pk_bf16_f32 v64, v64, v65
	v_cvt_pk_bf16_f32 v65, v66, v67
	global_store_dwordx2 v[136:137], v[64:65], off offset:192
	v_pk_mul_f32 v[8:9], v[124:125], v[138:139] op_sel_hi:[1,0]
	v_pk_mul_f32 v[10:11], v[132:133], v[138:139] op_sel_hi:[1,0]
	v_pk_mul_f32 v[68:69], v[8:9], v[68:69]
	v_pk_mul_f32 v[70:71], v[10:11], v[70:71]
	v_cvt_pk_bf16_f32 v68, v68, v69
	v_cvt_pk_bf16_f32 v69, v70, v71
	global_store_dwordx2 v[136:137], v[68:69], off offset:208
	v_pk_mul_f32 v[8:9], v[122:123], v[138:139] op_sel_hi:[1,0]
	v_pk_mul_f32 v[10:11], v[130:131], v[138:139] op_sel_hi:[1,0]
	v_pk_mul_f32 v[72:73], v[8:9], v[72:73]
	v_pk_mul_f32 v[74:75], v[10:11], v[74:75]
	v_cvt_pk_bf16_f32 v72, v72, v73
	v_cvt_pk_bf16_f32 v73, v74, v75
	global_store_dwordx2 v[136:137], v[72:73], off offset:224
	v_pk_mul_f32 v[8:9], v[120:121], v[138:139] op_sel_hi:[1,0]
	v_pk_mul_f32 v[10:11], v[126:127], v[138:139] op_sel_hi:[1,0]
	v_pk_mul_f32 v[76:77], v[8:9], v[76:77]
	v_pk_mul_f32 v[78:79], v[10:11], v[78:79]
	v_cvt_pk_bf16_f32 v76, v76, v77
	v_cvt_pk_bf16_f32 v77, v78, v79
	global_store_dwordx2 v[136:137], v[76:77], off offset:240
	s_cbranch_execnz .LBB0_104
	s_branch .LBB0_135
